# P0: tile->LDS barrier moved below the next item decode and loads (loads issued one barrier earlier)
# speedup vs baseline: 1.0052x; 1.0052x over previous
; __device__ __forceinline__ unsigned cvt_pk_bf16(float lo, float hi) { unsigned r; asm volatile("v_cvt_pk_bf16_f32 %0, %1, %2" : "=v"(r) : "v"(lo), "v"(hi)); return r; }
; #define LAS __attribute__((address_space(3)))
; __device__ __forceinline__ void p0_out(const P0Desc& d, const LAS float* T, int wid, int lane) {
;     const int c8 = lane & 7;
; #pragma unroll
;     for (int j = 0; j < 4; ++j) { const int n = (lane >> 3) + 8 * j; const int sc = d.perm ? pg8::perm32(n) : n; const LAS float* sp = T + (8 * c8) * 257 + 32 * wid + sc;
;         u32x4 o; o.x = cvt_pk_bf16(sp[0 * 257], sp[1 * 257]); o.y = cvt_pk_bf16(sp[2 * 257], sp[3 * 257]); o.z = cvt_pk_bf16(sp[4 * 257], sp[5 * 257]); o.w = cvt_pk_bf16(sp[6 * 257], sp[7 * 257]);
;         *(u32x4*)(d.dst + (size_t)n * d.K + 8 * c8) = o; }
; }
; __global__ void __launch_bounds__(NTHR, 2) fwd_kernel(Args a) {
;     ...
;           while (have) {
;               p0_to_lds(dc, tv, T, wid, lane);
;               __syncthreads();
;               const bool hn = p0_decode(it + G, ts, wid, lane, dn); if (hn) p0_load(dn, tv);
;               p0_out(dc, T, wid, lane);
;               __syncthreads();
;               have = hn; it += G; dc = dn;
.Lp0_nogain_b:
.LBB0_85:
	s_waitcnt lgkmcnt(0)
	s_barrier
	v_cndmask_b32_e64 v46, v34, v43, s[18:19]
	v_lshl_add_u32 v46, v46, 2, v41
	ds_read_b32 v51, v46 offset:1028
	ds_read_b32 v52, v46
	v_cndmask_b32_e64 v55, v38, v47, s[18:19]
	v_lshl_add_u32 v58, v55, 2, v41
	v_mad_i64_i32 v[56:57], s[36:37], s51, v34, 0
	s_waitcnt lgkmcnt(0)
	v_cvt_pk_bf16_f32 v52, v52, v51
	ds_read_b32 v51, v46 offset:3084
	ds_read_b32 v53, v46 offset:2056
	v_lshl_add_u64 v[56:57], v[56:57], 1, s[20:21]
	v_lshl_add_u64 v[56:57], v[56:57], 0, v[36:37]
	s_add_i32 s55, s55, s82
	s_waitcnt lgkmcnt(0)
	v_cvt_pk_bf16_f32 v53, v53, v51
	ds_read_b32 v51, v46 offset:5140
	ds_read_b32 v54, v46 offset:4112
	s_and_b64 vcc, exec, s[6:7]
	s_mov_b32 s43, s56
	s_waitcnt lgkmcnt(0)
	v_cvt_pk_bf16_f32 v54, v54, v51
	ds_read_b32 v51, v46 offset:7196
	ds_read_b32 v46, v46 offset:6168
	s_waitcnt lgkmcnt(0)
	v_cvt_pk_bf16_f32 v55, v46, v51
	ds_read_b32 v46, v58 offset:1028
	ds_read_b32 v51, v58
	global_store_dwordx4 v[56:57], v[52:55], off
	v_mad_i64_i32 v[56:57], s[36:37], s51, v38, 0
	s_waitcnt lgkmcnt(0)
	v_cvt_pk_bf16_f32 v52, v51, v46
	ds_read_b32 v46, v58 offset:3084
	ds_read_b32 v51, v58 offset:2056
	s_waitcnt lgkmcnt(0)
	v_cvt_pk_bf16_f32 v53, v51, v46
	ds_read_b32 v46, v58 offset:5140
	ds_read_b32 v51, v58 offset:4112
	s_waitcnt lgkmcnt(0)
	v_cvt_pk_bf16_f32 v54, v51, v46
	ds_read_b32 v46, v58 offset:7196
	ds_read_b32 v51, v58 offset:6168
	v_cndmask_b32_e64 v55, v40, v48, s[18:19]
	v_lshl_add_u32 v58, v55, 2, v41
	s_waitcnt lgkmcnt(0)
	v_cvt_pk_bf16_f32 v55, v51, v46
	ds_read_b32 v46, v58 offset:1028
	ds_read_b32 v51, v58
	v_lshl_add_u64 v[56:57], v[56:57], 1, s[20:21]
	v_lshl_add_u64 v[56:57], v[56:57], 0, v[36:37]
	global_store_dwordx4 v[56:57], v[52:55], off
	s_waitcnt lgkmcnt(0)
	s_nop 0
	v_cvt_pk_bf16_f32 v52, v51, v46
	ds_read_b32 v46, v58 offset:3084
	ds_read_b32 v51, v58 offset:2056
	s_waitcnt lgkmcnt(0)
	v_cvt_pk_bf16_f32 v53, v51, v46
	ds_read_b32 v46, v58 offset:5140
	ds_read_b32 v51, v58 offset:4112
	s_waitcnt lgkmcnt(0)
	v_cvt_pk_bf16_f32 v54, v51, v46
	ds_read_b32 v46, v58 offset:7196
	ds_read_b32 v51, v58 offset:6168
	v_cndmask_b32_e64 v55, v42, v49, s[18:19]
	v_lshl_add_u32 v58, v55, 2, v41
	s_waitcnt lgkmcnt(0)
	v_cvt_pk_bf16_f32 v55, v51, v46
	ds_read_b32 v46, v58 offset:1028
	ds_read_b32 v51, v58
	v_mad_i64_i32 v[56:57], s[18:19], s51, v40, 0
	v_lshl_add_u64 v[56:57], v[56:57], 1, s[20:21]
	v_lshl_add_u64 v[56:57], v[56:57], 0, v[36:37]
	global_store_dwordx4 v[56:57], v[52:55], off
	v_mad_i64_i32 v[56:57], s[18:19], s51, v42, 0
	s_waitcnt lgkmcnt(0)
	v_cvt_pk_bf16_f32 v52, v51, v46
	ds_read_b32 v46, v58 offset:3084
	ds_read_b32 v51, v58 offset:2056
	s_waitcnt lgkmcnt(0)
	v_cvt_pk_bf16_f32 v53, v51, v46
	ds_read_b32 v46, v58 offset:5140
	ds_read_b32 v51, v58 offset:4112
	s_waitcnt lgkmcnt(0)
	v_cvt_pk_bf16_f32 v54, v51, v46
	ds_read_b32 v46, v58 offset:7196
	ds_read_b32 v51, v58 offset:6168
	v_lshl_add_u64 v[56:57], v[56:57], 1, s[20:21]
	s_mov_b64 s[18:19], s[28:29]
	s_mov_b32 s51, s42
	v_lshl_add_u64 v[56:57], v[56:57], 0, v[36:37]
	s_mov_b64 s[20:21], s[34:35]
	s_waitcnt lgkmcnt(0)
	v_cvt_pk_bf16_f32 v55, v51, v46
	global_store_dwordx4 v[56:57], v[52:55], off
	s_barrier
	s_cbranch_vccnz .LBB0_149

; #define LAS __attribute__((address_space(3)))
; #define w_in ((const float*)KPTR(6))
; __device__ __forceinline__ bool p0_decode(int it, const P0Src& t, int wid, int lane, P0Desc& d) {
;     if (it >= 2 * P0_I_L) return false;
;     const int l = it / P0_I_L; int rr = it - l * P0_I_L; const float* W; int ldw, nv, K, blk, kb, dg; bf16_t* WT; bool perm; const float* gk = nullptr;
;     if (rr < P0_I_IN) { blk = rr >> 5; kb = rr & 31; const int sg = blk * 8 + wid; W = t.w_in + (size_t)l * DM * INC; ldw = INC; nv = INC; K = DM; WT = t.WT_IN + (size_t)l * INP * DM; gk = t.g_mix + (size_t)l * DM;
;         if (sg < 32) { dg = 64 + sg; perm = true; } else if (sg < 64) { const int q = sg - 32; dg = (q >> 2) * 8 + (q & 3); perm = true; } else if (sg < 96) { const int q = sg - 64; dg = (q >> 2) * 8 + 4 + (q & 3); perm = true; }
;         else { dg = sg; perm = sg < 192; } }
;     else if ((rr -= P0_I_IN) < P0_I_OUT) { blk = rr >> 5; kb = rr & 31; dg = blk * 8 + wid; perm = true; W = t.w_out + (size_t)l * DM * DM; ldw = DM; nv = DM; K = DM; WT = t.WT_OUT + (size_t)l * DM * DM; }
;     else if ((rr -= P0_I_OUT) < P0_I_UP) { blk = rr >> 5; kb = rr & 31; const int sg = blk * 8 + wid; perm = true; W = t.w_up + (size_t)l * DM * UPN; ldw = UPN; nv = UPN; K = DM; WT = t.WT_UP + (size_t)l * UPN * DM; gk = t.g_ffn + (size_t)l * DM;
;         if (sg < 176) dg = (sg >> 2) * 8 + (sg & 3); else { const int q = sg - 176; dg = (q >> 2) * 8 + 4 + (q & 3); } }
;     else { rr -= P0_I_UP; blk = rr / 88; kb = rr - blk * 88; dg = blk * 8 + wid; perm = true; W = t.w_down + (size_t)l * DFF * DM; ldw = DM; nv = DM; K = DFF; WT = t.WT_DN + (size_t)l * DM * DFF; }
;     const int k0 = 64 * kb, c = blk * 256 + 4 * lane;
;     d.ok = c < nv; d.src = W + (size_t)(k0 + wid * 8) * ldw + c; d.ldw = (size_t)ldw; d.gk = gk ? gk + k0 + wid * 8 : nullptr; d.dst = WT + (size_t)(dg * 32) * K + k0; d.K = K; d.perm = perm; return true;
; __device__ __forceinline__ void p0_to_lds(const P0Desc& d, const f32x4 (&tv)[8], LAS float* T, int wid, int lane) {
; #pragma unroll
;     for (int i = 0; i < 8; ++i) { const float g = d.gk ? d.gk[i] : 1.f; LAS float* tp = T + (wid * 8 + i) * 257 + 4 * lane; tp[0] = tv[i].x * g; tp[1] = tv[i].y * g; tp[2] = tv[i].z * g; tp[3] = tv[i].w * g; }
; }
.LBB0_98:
	s_add_i32 s56, s43, s82
	s_cmpk_lt_i32 s56, 0x18c0
	s_cselect_b64 s[36:37], -1, 0
	s_cmpk_gt_i32 s56, 0x18bf
	v_pk_mul_f32 v[52:53], v[24:25], v[46:47] op_sel_hi:[1,0]
	v_add_u32_e32 v51, 0x1c1c, v50
	s_cselect_b64 s[6:7], -1, 0
	ds_write2_b32 v51, v52, v53 offset1:1
	v_pk_mul_f32 v[52:53], v[26:27], v[46:47] op_sel_hi:[1,0]
	v_add_u32_e32 v46, 0x1c24, v50
	s_and_b64 vcc, exec, s[6:7]
	ds_write2_b32 v46, v52, v53 offset1:1
	s_cbranch_vccnz .LBB0_127
	s_mul_hi_i32 s22, s56, 0xa57eb503
	s_add_i32 s22, s22, s56
	s_lshr_b32 s26, s22, 31
	s_ashr_i32 s22, s22, 11
	s_add_i32 s30, s22, s26
	s_mul_i32 s22, s30, 0xfffff3a0
	s_add_i32 s59, s56, s22
	s_mov_b64 s[28:29], -1
	s_cmpk_gt_i32 s59, 0x31f
	s_mov_b64 s[40:41], -1
	s_cbranch_scc0 .LBB0_112
	s_cmpk_gt_u32 s59, 0x41f
	s_cbranch_scc0 .LBB0_109
	s_mov_b64 s[38:39], -1
	s_cmpk_gt_u32 s59, 0x99f
	s_mul_hi_i32 s22, s30, 0x2c00000
	s_mul_i32 s42, s30, 0x2c00000
	s_cbranch_scc0 .LBB0_103
	s_add_i32 s26, s59, 0xfffff660
	s_mul_hi_u32 s26, s26, 0xba2e8ba3
	s_lshr_b32 s57, s26, 6
	s_mul_i32 s26, s30, 0xc60
	s_sub_i32 s27, s55, s26
	s_mul_hi_u32 s27, s27, 0xba2e8ba3
	s_lshr_b32 s27, s27, 6
	s_mulk_i32 s27, 0xffa8
	s_sub_i32 s26, s27, s26
	s_add_i32 s27, s54, s43
	s_add_i32 s60, s27, s26
	s_lshl_b32 s26, s57, 3
	s_add_i32 s58, s26, s33
	s_add_u32 s26, s16, s42
	s_addc_u32 s27, s17, s22
	s_mul_i32 s34, s30, 0x1600000
	s_mul_hi_i32 s31, s30, 0x1600000
	s_add_u32 s34, s49, s34
	s_addc_u32 s35, s50, s31
	s_mov_b64 s[38:39], 0
